# v42: v41 + first pre-norm phase write-through with flat barrier
# baseline (speedup 1.0000x reference)
.LBB0_338:
	s_cmp_lt_i32 s59, 3
	s_barrier
	s_cbranch_scc1 .LBB0_392
	s_waitcnt vmcnt(0)
	s_barrier
	s_and_saveexec_b64 s[2:3], s[0:1]
	s_cbranch_execz .LBB0_391
	s_waitcnt vmcnt(0) lgkmcnt(0)
	v_mov_b32_e32 v241, 0
	v_lshlrev_b32_e64 v254, 8, s31
	v_mov_b32_e32 v247, 1
	v_mov_b32_e32 v246, 0x3600
	global_atomic_add v248, v246, v247, s[60:61] sc0
	buffer_inv sc1
